# v59 + hand-written P2 short-conv branch body: all row loads of each 8-row half issued up front with counted waits (was 4 exposed load latencies per item)
# speedup vs baseline: 1.0041x; 1.0041x over previous
; __device__ __forceinline__ unsigned cvt_pk_bf16(float lo, float hi) { unsigned r; asm volatile("v_cvt_pk_bf16_f32 %0, %1, %2" : "=v"(r) : "v"(lo), "v"(hi)); return r; }
; __device__ __forceinline__ void convbranch_phase(const bf16* proj, bf16* yc, const float* cw, const float* cb, int T, int vcu, int NT) {
;     ...
;     for (int item = gtid; item < NG * R; item += NT) {
;         const int run = item / NG, ch = (item - run * NG) * 8, t0 = run * L;
;         float w0[8], w1[8], w2[8], bb[8];
; #pragma unroll
;         for (int e = 0; e < 8; e += 4) { *(f32x4*)(w0 + e) = *(const f32x4*)(cw + ch + e); *(f32x4*)(w1 + e) = *(const f32x4*)(cw + AW + ch + e);
;             *(f32x4*)(w2 + e) = *(const f32x4*)(cw + 2 * AW + ch + e); *(f32x4*)(bb + e) = *(const f32x4*)(cb + ch + e); }
;         const bf16* p = proj + (size_t)t0 * PW + ch;
;         float pp[8], pc[8], fu[8], fc[8];
;         unpack8(*(const v4u*)(p + C_GCU), pc);
;         if (t0 > 0) unpack8(*(const v4u*)(p - PW + C_GCU), pp);
;         else {
; #pragma unroll
;           for (int e = 0; e < 8; ++e) pp[e] = 0.f; }
;         for (int t = t0; t < t0 + L; t += 4) {
;             const v4u z4 = (v4u){0u, 0u, 0u, 0u}; v4u un[4], gq[4];
; #pragma unroll
;             for (int q = 0; q < 4; ++q) { un[q] = z4; gq[q] = *(const v4u*)(p + (size_t)q * PW + C_GB);
;                 if (t + q + 1 < MC) un[q] = *(const v4u*)(p + (size_t)(q + 1) * PW + C_GCU); }
; #pragma unroll
;             for (int q = 0; q < 4; ++q) { const int tpos = (t + q) & (T - 1);
;                 float fg[8], pn[8], r[8]; unpack8(gq[q], fg); unpack8(un[q], pn);
;                 const float mp = tpos == 0 ? 0.f : 1.f, mn = tpos == T - 1 ? 0.f : 1.f;
; #pragma unroll
;                 for (int e = 0; e < 8; ++e) { r[e] = fg[e] * (w0[e] * (pp[e] * mp) + w1[e] * pc[e] + w2[e] * (pn[e] * mn) + bb[e]); pp[e] = pc[e]; pc[e] = pn[e]; }
;                 v4u o; o.x = cvt_pk_bf16(r[0], r[1]); o.y = cvt_pk_bf16(r[2], r[3]); o.z = cvt_pk_bf16(r[4], r[5]); o.w = cvt_pk_bf16(r[6], r[7]);
;                 *(v4u*)(yc + (size_t)(t + q) * AW + ch) = o; }
.LBB0_566:
	v_ashrrev_i32_e32 v1, 31, v154
	v_lshrrev_b32_e32 v1, 26, v1
	v_add_u32_e32 v1, v154, v1
	v_ashrrev_i32_e32 v1, 6, v1
	v_lshlrev_b32_e32 v40, 9, v1
	v_lshlrev_b32_e32 v2, 3, v154
	v_sub_u32_e32 v34, v2, v40
	v_ashrrev_i32_e32 v35, 31, v34
	v_lshlrev_b64 v[2:3], 2, v[34:35]
	v_lshl_add_u64 v[14:15], s[18:19], 0, v[2:3]
	v_lshl_add_u64 v[22:23], s[30:31], 0, v[2:3]
	v_lshl_add_u64 v[30:31], s[22:23], 0, v[2:3]
	global_load_dwordx4 v[2:5], v[14:15], off offset:16
	global_load_dwordx4 v[6:9], v[14:15], off
	global_load_dwordx4 v[10:13], v[14:15], off offset:2064
	s_nop 0
	global_load_dwordx4 v[14:17], v[14:15], off offset:2048
	s_nop 0
	global_load_dwordx4 v[18:21], v[22:23], off offset:16
	s_nop 0
	global_load_dwordx4 v[22:25], v[22:23], off
	s_nop 0
	global_load_dwordx4 v[26:29], v[30:31], off offset:16
	s_nop 0
	global_load_dwordx4 v[30:33], v[30:31], off
	v_lshlrev_b32_e32 v66, 4, v1
	v_mov_b64_e32 v[36:37], s[66:67]
	v_mad_i64_i32 v[36:37], s[24:25], v66, s55, v[36:37]
	v_lshl_add_u64 v[38:39], v[34:35], 1, v[36:37]
	v_lshlrev_b32_e32 v42, 10, v66
	v_lshl_add_u32 v42, v34, 1, v42
	v_mov_b32_e32 v41, s59
	v_add_co_u32_e32 v40, vcc, s58, v42
	v_addc_co_u32_e32 v41, vcc, 0, v41, vcc
	v_add_co_u32_e32 v40, vcc, 0x1e000000, v40
	v_addc_co_u32_e32 v41, vcc, 0, v41, vcc
	v_mov_b32_e32 v96, 0
	v_mov_b32_e32 v97, 0
	v_mov_b32_e32 v98, 0
	v_mov_b32_e32 v99, 0
	v_mov_b32_e32 v100, 0
	v_mov_b32_e32 v101, 0
	v_mov_b32_e32 v102, 0
	v_mov_b32_e32 v103, 0
	v_and_b32_e32 v43, s88, v66
	v_cmp_ne_u32_e32 vcc, 0, v43
	s_mov_b64 s[40:41], 0
	s_nop 0
	s_and_saveexec_b64 s[40:41], vcc
	v_add_co_u32_e32 v36, vcc, 0xffffdc00, v38
	v_addc_co_u32_e32 v37, vcc, -1, v39, vcc
	global_load_dwordx4 v[96:99], v[36:37], off offset:2048
	s_or_b64 exec, exec, s[40:41]
	v_add_u32_e32 v43, 16, v66
	v_and_b32_e32 v43, s88, v43
	v_cmp_ne_u32_e32 vcc, 0, v43
	s_nop 1
	s_and_saveexec_b64 s[40:41], vcc
	v_add_co_u32_e32 v36, vcc, 0x24000, v38
	v_addc_co_u32_e32 v37, vcc, 0, v39, vcc
	global_load_dwordx4 v[100:103], v[36:37], off offset:2048
	s_or_b64 exec, exec, s[40:41]
	s_mov_b64 s[40:41], 0
	v_mov_b32_e32 v36, v38
	v_mov_b32_e32 v37, v39
	global_load_dwordx4 v[104:107], v[36:37], off offset:2048
	global_load_dwordx4 v[140:143], v[36:37], off offset:3072
	v_add_co_u32_e32 v36, vcc, 0x2400, v36
	v_addc_co_u32_e32 v37, vcc, 0, v37, vcc
	global_load_dwordx4 v[108:111], v[36:37], off offset:2048
	global_load_dwordx4 v[144:147], v[36:37], off offset:3072
	v_add_co_u32_e32 v36, vcc, 0x2400, v36
	v_addc_co_u32_e32 v37, vcc, 0, v37, vcc
	global_load_dwordx4 v[112:115], v[36:37], off offset:2048
	global_load_dwordx4 v[148:151], v[36:37], off offset:3072
	v_add_co_u32_e32 v36, vcc, 0x2400, v36
	v_addc_co_u32_e32 v37, vcc, 0, v37, vcc
	global_load_dwordx4 v[116:119], v[36:37], off offset:2048
	global_load_dwordx4 v[156:159], v[36:37], off offset:3072
	v_add_co_u32_e32 v36, vcc, 0x2400, v36
	v_addc_co_u32_e32 v37, vcc, 0, v37, vcc
	global_load_dwordx4 v[120:123], v[36:37], off offset:2048
	global_load_dwordx4 v[174:177], v[36:37], off offset:3072
	v_add_co_u32_e32 v36, vcc, 0x2400, v36
	v_addc_co_u32_e32 v37, vcc, 0, v37, vcc
	global_load_dwordx4 v[124:127], v[36:37], off offset:2048
	global_load_dwordx4 v[204:207], v[36:37], off offset:3072
	v_add_co_u32_e32 v36, vcc, 0x2400, v36
	v_addc_co_u32_e32 v37, vcc, 0, v37, vcc
	global_load_dwordx4 v[128:131], v[36:37], off offset:2048
	global_load_dwordx4 v[214:217], v[36:37], off offset:3072
	v_add_co_u32_e32 v36, vcc, 0x2400, v36
	v_addc_co_u32_e32 v37, vcc, 0, v37, vcc
	global_load_dwordx4 v[132:135], v[36:37], off offset:2048
	global_load_dwordx4 v[218:221], v[36:37], off offset:3072
	v_add_co_u32_e32 v36, vcc, 0x2400, v36
	v_addc_co_u32_e32 v37, vcc, 0, v37, vcc
	global_load_dwordx4 v[136:139], v[36:37], off offset:2048
	s_waitcnt vmcnt(16)
	v_lshlrev_b32_e32 v64, 16, v96
	v_and_b32_e32 v65, 0xffff0000, v96
	v_lshlrev_b32_e32 v66, 16, v97
	v_and_b32_e32 v67, 0xffff0000, v97
	v_lshlrev_b32_e32 v68, 16, v98
	v_and_b32_e32 v69, 0xffff0000, v98
	v_lshlrev_b32_e32 v70, 16, v99
	v_and_b32_e32 v71, 0xffff0000, v99
	v_lshlrev_b32_e32 v72, 16, v104
	v_and_b32_e32 v73, 0xffff0000, v104
	v_lshlrev_b32_e32 v74, 16, v105
	v_and_b32_e32 v75, 0xffff0000, v105
	v_lshlrev_b32_e32 v76, 16, v106
	v_and_b32_e32 v77, 0xffff0000, v106
	v_lshlrev_b32_e32 v78, 16, v107
	v_and_b32_e32 v79, 0xffff0000, v107
	s_waitcnt vmcnt(14)
	v_lshlrev_b32_e32 v80, 16, v108
	v_and_b32_e32 v81, 0xffff0000, v108
	v_lshlrev_b32_e32 v82, 16, v109
	v_and_b32_e32 v83, 0xffff0000, v109
	v_lshlrev_b32_e32 v84, 16, v110
	v_and_b32_e32 v85, 0xffff0000, v110
	v_lshlrev_b32_e32 v86, 16, v111
	v_and_b32_e32 v87, 0xffff0000, v111
	v_lshlrev_b32_e32 v88, 16, v140
	v_and_b32_e32 v89, 0xffff0000, v140
	v_lshlrev_b32_e32 v90, 16, v141
	v_and_b32_e32 v91, 0xffff0000, v141
	v_lshlrev_b32_e32 v92, 16, v142
	v_and_b32_e32 v93, 0xffff0000, v142
	v_lshlrev_b32_e32 v94, 16, v143
	v_and_b32_e32 v95, 0xffff0000, v143
	v_pk_mul_f32 v[48:49], v[14:15], v[72:73]
	v_pk_mul_f32 v[56:57], v[22:23], v[80:81]
	v_pk_fma_f32 v[48:49], v[6:7], v[64:65], v[48:49]
	v_pk_add_f32 v[48:49], v[48:49], v[56:57]
	v_pk_add_f32 v[48:49], v[30:31], v[48:49]
	v_pk_mul_f32 v[48:49], v[48:49], v[88:89]
	v_pk_mul_f32 v[50:51], v[16:17], v[74:75]
	v_pk_mul_f32 v[56:57], v[24:25], v[82:83]
	v_pk_fma_f32 v[50:51], v[8:9], v[66:67], v[50:51]
	v_pk_add_f32 v[50:51], v[50:51], v[56:57]
	v_pk_add_f32 v[50:51], v[32:33], v[50:51]
	v_pk_mul_f32 v[50:51], v[50:51], v[90:91]
	v_pk_mul_f32 v[52:53], v[10:11], v[76:77]
	v_pk_mul_f32 v[56:57], v[18:19], v[84:85]
	v_pk_fma_f32 v[52:53], v[2:3], v[68:69], v[52:53]
	v_pk_add_f32 v[52:53], v[52:53], v[56:57]
	v_pk_add_f32 v[52:53], v[26:27], v[52:53]
	v_pk_mul_f32 v[52:53], v[52:53], v[92:93]
	v_pk_mul_f32 v[54:55], v[12:13], v[78:79]
	v_pk_mul_f32 v[56:57], v[20:21], v[86:87]
	v_pk_fma_f32 v[54:55], v[4:5], v[70:71], v[54:55]
	v_pk_add_f32 v[54:55], v[54:55], v[56:57]
	v_pk_add_f32 v[54:55], v[28:29], v[54:55]
	v_pk_mul_f32 v[54:55], v[54:55], v[94:95]
	v_cvt_pk_bf16_f32 v42, v48, v49
	v_cvt_pk_bf16_f32 v43, v50, v51
	v_cvt_pk_bf16_f32 v44, v52, v53
	v_cvt_pk_bf16_f32 v45, v54, v55
	global_store_dwordx4 v[40:41], v[42:45], off
	s_waitcnt vmcnt(13)
; __device__ __forceinline__ unsigned cvt_pk_bf16(float lo, float hi) { unsigned r; asm volatile("v_cvt_pk_bf16_f32 %0, %1, %2" : "=v"(r) : "v"(lo), "v"(hi)); return r; }
; __device__ __forceinline__ void convbranch_phase(const bf16* proj, bf16* yc, const float* cw, const float* cb, int T, int vcu, int NT) {
;     ...
;             for (int q = 0; q < 4; ++q) { const int tpos = (t + q) & (T - 1);
;                 float fg[8], pn[8], r[8]; unpack8(gq[q], fg); unpack8(un[q], pn);
;                 const float mp = tpos == 0 ? 0.f : 1.f, mn = tpos == T - 1 ? 0.f : 1.f;
; #pragma unroll
;                 for (int e = 0; e < 8; ++e) { r[e] = fg[e] * (w0[e] * (pp[e] * mp) + w1[e] * pc[e] + w2[e] * (pn[e] * mn) + bb[e]); pp[e] = pc[e]; pc[e] = pn[e]; }
;                 v4u o; o.x = cvt_pk_bf16(r[0], r[1]); o.y = cvt_pk_bf16(r[2], r[3]); o.z = cvt_pk_bf16(r[4], r[5]); o.w = cvt_pk_bf16(r[6], r[7]);
;                 *(v4u*)(yc + (size_t)(t + q) * AW + ch) = o; }
	v_lshlrev_b32_e32 v64, 16, v112
	v_and_b32_e32 v65, 0xffff0000, v112
	v_lshlrev_b32_e32 v66, 16, v113
	v_and_b32_e32 v67, 0xffff0000, v113
	v_lshlrev_b32_e32 v68, 16, v114
	v_and_b32_e32 v69, 0xffff0000, v114
	v_lshlrev_b32_e32 v70, 16, v115
	v_and_b32_e32 v71, 0xffff0000, v115
	v_lshlrev_b32_e32 v88, 16, v144
	v_and_b32_e32 v89, 0xffff0000, v144
	v_lshlrev_b32_e32 v90, 16, v145
	v_and_b32_e32 v91, 0xffff0000, v145
	v_lshlrev_b32_e32 v92, 16, v146
	v_and_b32_e32 v93, 0xffff0000, v146
	v_lshlrev_b32_e32 v94, 16, v147
	v_and_b32_e32 v95, 0xffff0000, v147
	v_pk_mul_f32 v[48:49], v[14:15], v[80:81]
	v_pk_mul_f32 v[56:57], v[22:23], v[64:65]
	v_pk_fma_f32 v[48:49], v[6:7], v[72:73], v[48:49]
	v_pk_add_f32 v[48:49], v[48:49], v[56:57]
	v_pk_add_f32 v[48:49], v[30:31], v[48:49]
	v_pk_mul_f32 v[48:49], v[48:49], v[88:89]
	v_pk_mul_f32 v[50:51], v[16:17], v[82:83]
	v_pk_mul_f32 v[56:57], v[24:25], v[66:67]
	v_pk_fma_f32 v[50:51], v[8:9], v[74:75], v[50:51]
	v_pk_add_f32 v[50:51], v[50:51], v[56:57]
	v_pk_add_f32 v[50:51], v[32:33], v[50:51]
	v_pk_mul_f32 v[50:51], v[50:51], v[90:91]
	v_pk_mul_f32 v[52:53], v[10:11], v[84:85]
	v_pk_mul_f32 v[56:57], v[18:19], v[68:69]
	v_pk_fma_f32 v[52:53], v[2:3], v[76:77], v[52:53]
	v_pk_add_f32 v[52:53], v[52:53], v[56:57]
	v_pk_add_f32 v[52:53], v[26:27], v[52:53]
	v_pk_mul_f32 v[52:53], v[52:53], v[92:93]
	v_pk_mul_f32 v[54:55], v[12:13], v[86:87]
	v_pk_mul_f32 v[56:57], v[20:21], v[70:71]
	v_pk_fma_f32 v[54:55], v[4:5], v[78:79], v[54:55]
	v_pk_add_f32 v[54:55], v[54:55], v[56:57]
	v_pk_add_f32 v[54:55], v[28:29], v[54:55]
	v_pk_mul_f32 v[54:55], v[54:55], v[94:95]
	v_cvt_pk_bf16_f32 v58, v48, v49
	v_cvt_pk_bf16_f32 v59, v50, v51
	v_cvt_pk_bf16_f32 v60, v52, v53
	v_cvt_pk_bf16_f32 v61, v54, v55
	global_store_dwordx4 v[40:41], v[58:61], off offset:1024
	s_waitcnt vmcnt(12)
	v_lshlrev_b32_e32 v72, 16, v116
	v_and_b32_e32 v73, 0xffff0000, v116
	v_lshlrev_b32_e32 v74, 16, v117
	v_and_b32_e32 v75, 0xffff0000, v117
	v_lshlrev_b32_e32 v76, 16, v118
	v_and_b32_e32 v77, 0xffff0000, v118
	v_lshlrev_b32_e32 v78, 16, v119
	v_and_b32_e32 v79, 0xffff0000, v119
	v_lshlrev_b32_e32 v88, 16, v148
	v_and_b32_e32 v89, 0xffff0000, v148
	v_lshlrev_b32_e32 v90, 16, v149
	v_and_b32_e32 v91, 0xffff0000, v149
	v_lshlrev_b32_e32 v92, 16, v150
	v_and_b32_e32 v93, 0xffff0000, v150
	v_lshlrev_b32_e32 v94, 16, v151
	v_and_b32_e32 v95, 0xffff0000, v151
	v_pk_mul_f32 v[48:49], v[14:15], v[64:65]
	v_pk_mul_f32 v[56:57], v[22:23], v[72:73]
	v_pk_fma_f32 v[48:49], v[6:7], v[80:81], v[48:49]
	v_pk_add_f32 v[48:49], v[48:49], v[56:57]
	v_pk_add_f32 v[48:49], v[30:31], v[48:49]
	v_pk_mul_f32 v[48:49], v[48:49], v[88:89]
	v_pk_mul_f32 v[50:51], v[16:17], v[66:67]
	v_pk_mul_f32 v[56:57], v[24:25], v[74:75]
	v_pk_fma_f32 v[50:51], v[8:9], v[82:83], v[50:51]
	v_pk_add_f32 v[50:51], v[50:51], v[56:57]
	v_pk_add_f32 v[50:51], v[32:33], v[50:51]
	v_pk_mul_f32 v[50:51], v[50:51], v[90:91]
	v_pk_mul_f32 v[52:53], v[10:11], v[68:69]
	v_pk_mul_f32 v[56:57], v[18:19], v[76:77]
	v_pk_fma_f32 v[52:53], v[2:3], v[84:85], v[52:53]
	v_pk_add_f32 v[52:53], v[52:53], v[56:57]
	v_pk_add_f32 v[52:53], v[26:27], v[52:53]
	v_pk_mul_f32 v[52:53], v[52:53], v[92:93]
	v_pk_mul_f32 v[54:55], v[12:13], v[70:71]
	v_pk_mul_f32 v[56:57], v[20:21], v[78:79]
	v_pk_fma_f32 v[54:55], v[4:5], v[86:87], v[54:55]
	v_pk_add_f32 v[54:55], v[54:55], v[56:57]
	v_pk_add_f32 v[54:55], v[28:29], v[54:55]
	v_pk_mul_f32 v[54:55], v[54:55], v[94:95]
	v_cvt_pk_bf16_f32 v42, v48, v49
	v_cvt_pk_bf16_f32 v43, v50, v51
	v_cvt_pk_bf16_f32 v44, v52, v53
	v_cvt_pk_bf16_f32 v45, v54, v55
	global_store_dwordx4 v[40:41], v[42:45], off offset:2048
	s_waitcnt vmcnt(11)
	v_lshlrev_b32_e32 v80, 16, v120
	v_and_b32_e32 v81, 0xffff0000, v120
	v_lshlrev_b32_e32 v82, 16, v121
	v_and_b32_e32 v83, 0xffff0000, v121
	v_lshlrev_b32_e32 v84, 16, v122
	v_and_b32_e32 v85, 0xffff0000, v122
	v_lshlrev_b32_e32 v86, 16, v123
	v_and_b32_e32 v87, 0xffff0000, v123
	v_lshlrev_b32_e32 v88, 16, v156
	v_and_b32_e32 v89, 0xffff0000, v156
	v_lshlrev_b32_e32 v90, 16, v157
	v_and_b32_e32 v91, 0xffff0000, v157
	v_lshlrev_b32_e32 v92, 16, v158
	v_and_b32_e32 v93, 0xffff0000, v158
	v_lshlrev_b32_e32 v94, 16, v159
	v_and_b32_e32 v95, 0xffff0000, v159
	v_pk_mul_f32 v[48:49], v[14:15], v[72:73]
	v_pk_mul_f32 v[56:57], v[22:23], v[80:81]
	v_pk_fma_f32 v[48:49], v[6:7], v[64:65], v[48:49]
	v_pk_add_f32 v[48:49], v[48:49], v[56:57]
	v_pk_add_f32 v[48:49], v[30:31], v[48:49]
	v_pk_mul_f32 v[48:49], v[48:49], v[88:89]
	v_pk_mul_f32 v[50:51], v[16:17], v[74:75]
	v_pk_mul_f32 v[56:57], v[24:25], v[82:83]
	v_pk_fma_f32 v[50:51], v[8:9], v[66:67], v[50:51]
	v_pk_add_f32 v[50:51], v[50:51], v[56:57]
	v_pk_add_f32 v[50:51], v[32:33], v[50:51]
	v_pk_mul_f32 v[50:51], v[50:51], v[90:91]
	v_pk_mul_f32 v[52:53], v[10:11], v[76:77]
	v_pk_mul_f32 v[56:57], v[18:19], v[84:85]
	v_pk_fma_f32 v[52:53], v[2:3], v[68:69], v[52:53]
	v_pk_add_f32 v[52:53], v[52:53], v[56:57]
	v_pk_add_f32 v[52:53], v[26:27], v[52:53]
	v_pk_mul_f32 v[52:53], v[52:53], v[92:93]
	v_pk_mul_f32 v[54:55], v[12:13], v[78:79]
	v_pk_mul_f32 v[56:57], v[20:21], v[86:87]
	v_pk_fma_f32 v[54:55], v[4:5], v[70:71], v[54:55]
	v_pk_add_f32 v[54:55], v[54:55], v[56:57]
	v_pk_add_f32 v[54:55], v[28:29], v[54:55]
	v_pk_mul_f32 v[54:55], v[54:55], v[94:95]
	v_cvt_pk_bf16_f32 v58, v48, v49
	v_cvt_pk_bf16_f32 v59, v50, v51
	v_cvt_pk_bf16_f32 v60, v52, v53
	v_cvt_pk_bf16_f32 v61, v54, v55
	global_store_dwordx4 v[40:41], v[58:61], off offset:3072
	s_waitcnt vmcnt(10)
; __device__ __forceinline__ unsigned cvt_pk_bf16(float lo, float hi) { unsigned r; asm volatile("v_cvt_pk_bf16_f32 %0, %1, %2" : "=v"(r) : "v"(lo), "v"(hi)); return r; }
; __device__ __forceinline__ void convbranch_phase(const bf16* proj, bf16* yc, const float* cw, const float* cb, int T, int vcu, int NT) {
;     ...
;             for (int q = 0; q < 4; ++q) { const int tpos = (t + q) & (T - 1);
;                 float fg[8], pn[8], r[8]; unpack8(gq[q], fg); unpack8(un[q], pn);
;                 const float mp = tpos == 0 ? 0.f : 1.f, mn = tpos == T - 1 ? 0.f : 1.f;
; #pragma unroll
;                 for (int e = 0; e < 8; ++e) { r[e] = fg[e] * (w0[e] * (pp[e] * mp) + w1[e] * pc[e] + w2[e] * (pn[e] * mn) + bb[e]); pp[e] = pc[e]; pc[e] = pn[e]; }
;                 v4u o; o.x = cvt_pk_bf16(r[0], r[1]); o.y = cvt_pk_bf16(r[2], r[3]); o.z = cvt_pk_bf16(r[4], r[5]); o.w = cvt_pk_bf16(r[6], r[7]);
;                 *(v4u*)(yc + (size_t)(t + q) * AW + ch) = o; }
	v_lshlrev_b32_e32 v64, 16, v124
	v_and_b32_e32 v65, 0xffff0000, v124
	v_lshlrev_b32_e32 v66, 16, v125
	v_and_b32_e32 v67, 0xffff0000, v125
	v_lshlrev_b32_e32 v68, 16, v126
	v_and_b32_e32 v69, 0xffff0000, v126
	v_lshlrev_b32_e32 v70, 16, v127
	v_and_b32_e32 v71, 0xffff0000, v127
	v_lshlrev_b32_e32 v88, 16, v174
	v_and_b32_e32 v89, 0xffff0000, v174
	v_lshlrev_b32_e32 v90, 16, v175
	v_and_b32_e32 v91, 0xffff0000, v175
	v_lshlrev_b32_e32 v92, 16, v176
	v_and_b32_e32 v93, 0xffff0000, v176
	v_lshlrev_b32_e32 v94, 16, v177
	v_and_b32_e32 v95, 0xffff0000, v177
	v_pk_mul_f32 v[48:49], v[14:15], v[80:81]
	v_pk_mul_f32 v[56:57], v[22:23], v[64:65]
	v_pk_fma_f32 v[48:49], v[6:7], v[72:73], v[48:49]
	v_pk_add_f32 v[48:49], v[48:49], v[56:57]
	v_pk_add_f32 v[48:49], v[30:31], v[48:49]
	v_pk_mul_f32 v[48:49], v[48:49], v[88:89]
	v_pk_mul_f32 v[50:51], v[16:17], v[82:83]
	v_pk_mul_f32 v[56:57], v[24:25], v[66:67]
	v_pk_fma_f32 v[50:51], v[8:9], v[74:75], v[50:51]
	v_pk_add_f32 v[50:51], v[50:51], v[56:57]
	v_pk_add_f32 v[50:51], v[32:33], v[50:51]
	v_pk_mul_f32 v[50:51], v[50:51], v[90:91]
	v_pk_mul_f32 v[52:53], v[10:11], v[84:85]
	v_pk_mul_f32 v[56:57], v[18:19], v[68:69]
	v_pk_fma_f32 v[52:53], v[2:3], v[76:77], v[52:53]
	v_pk_add_f32 v[52:53], v[52:53], v[56:57]
	v_pk_add_f32 v[52:53], v[26:27], v[52:53]
	v_pk_mul_f32 v[52:53], v[52:53], v[92:93]
	v_pk_mul_f32 v[54:55], v[12:13], v[86:87]
	v_pk_mul_f32 v[56:57], v[20:21], v[70:71]
	v_pk_fma_f32 v[54:55], v[4:5], v[78:79], v[54:55]
	v_pk_add_f32 v[54:55], v[54:55], v[56:57]
	v_pk_add_f32 v[54:55], v[28:29], v[54:55]
	v_pk_mul_f32 v[54:55], v[54:55], v[94:95]
	v_cvt_pk_bf16_f32 v42, v48, v49
	v_cvt_pk_bf16_f32 v43, v50, v51
	v_cvt_pk_bf16_f32 v44, v52, v53
	v_cvt_pk_bf16_f32 v45, v54, v55
	v_add_co_u32_e32 v40, vcc, 0x1000, v40
	v_addc_co_u32_e32 v41, vcc, 0, v41, vcc
	global_store_dwordx4 v[40:41], v[42:45], off
	s_waitcnt vmcnt(9)
	v_lshlrev_b32_e32 v72, 16, v128
	v_and_b32_e32 v73, 0xffff0000, v128
	v_lshlrev_b32_e32 v74, 16, v129
	v_and_b32_e32 v75, 0xffff0000, v129
	v_lshlrev_b32_e32 v76, 16, v130
	v_and_b32_e32 v77, 0xffff0000, v130
	v_lshlrev_b32_e32 v78, 16, v131
	v_and_b32_e32 v79, 0xffff0000, v131
	v_lshlrev_b32_e32 v88, 16, v204
	v_and_b32_e32 v89, 0xffff0000, v204
	v_lshlrev_b32_e32 v90, 16, v205
	v_and_b32_e32 v91, 0xffff0000, v205
	v_lshlrev_b32_e32 v92, 16, v206
	v_and_b32_e32 v93, 0xffff0000, v206
	v_lshlrev_b32_e32 v94, 16, v207
	v_and_b32_e32 v95, 0xffff0000, v207
	v_pk_mul_f32 v[48:49], v[14:15], v[64:65]
	v_pk_mul_f32 v[56:57], v[22:23], v[72:73]
	v_pk_fma_f32 v[48:49], v[6:7], v[80:81], v[48:49]
	v_pk_add_f32 v[48:49], v[48:49], v[56:57]
	v_pk_add_f32 v[48:49], v[30:31], v[48:49]
	v_pk_mul_f32 v[48:49], v[48:49], v[88:89]
	v_pk_mul_f32 v[50:51], v[16:17], v[66:67]
	v_pk_mul_f32 v[56:57], v[24:25], v[74:75]
	v_pk_fma_f32 v[50:51], v[8:9], v[82:83], v[50:51]
	v_pk_add_f32 v[50:51], v[50:51], v[56:57]
	v_pk_add_f32 v[50:51], v[32:33], v[50:51]
	v_pk_mul_f32 v[50:51], v[50:51], v[90:91]
	v_pk_mul_f32 v[52:53], v[10:11], v[68:69]
	v_pk_mul_f32 v[56:57], v[18:19], v[76:77]
	v_pk_fma_f32 v[52:53], v[2:3], v[84:85], v[52:53]
	v_pk_add_f32 v[52:53], v[52:53], v[56:57]
	v_pk_add_f32 v[52:53], v[26:27], v[52:53]
	v_pk_mul_f32 v[52:53], v[52:53], v[92:93]
	v_pk_mul_f32 v[54:55], v[12:13], v[70:71]
	v_pk_mul_f32 v[56:57], v[20:21], v[78:79]
	v_pk_fma_f32 v[54:55], v[4:5], v[86:87], v[54:55]
	v_pk_add_f32 v[54:55], v[54:55], v[56:57]
	v_pk_add_f32 v[54:55], v[28:29], v[54:55]
	v_pk_mul_f32 v[54:55], v[54:55], v[94:95]
	v_cvt_pk_bf16_f32 v58, v48, v49
	v_cvt_pk_bf16_f32 v59, v50, v51
	v_cvt_pk_bf16_f32 v60, v52, v53
	v_cvt_pk_bf16_f32 v61, v54, v55
	global_store_dwordx4 v[40:41], v[58:61], off offset:1024
	s_waitcnt vmcnt(8)
	v_lshlrev_b32_e32 v80, 16, v132
	v_and_b32_e32 v81, 0xffff0000, v132
	v_lshlrev_b32_e32 v82, 16, v133
	v_and_b32_e32 v83, 0xffff0000, v133
	v_lshlrev_b32_e32 v84, 16, v134
	v_and_b32_e32 v85, 0xffff0000, v134
	v_lshlrev_b32_e32 v86, 16, v135
	v_and_b32_e32 v87, 0xffff0000, v135
	v_lshlrev_b32_e32 v88, 16, v214
	v_and_b32_e32 v89, 0xffff0000, v214
	v_lshlrev_b32_e32 v90, 16, v215
	v_and_b32_e32 v91, 0xffff0000, v215
	v_lshlrev_b32_e32 v92, 16, v216
	v_and_b32_e32 v93, 0xffff0000, v216
	v_lshlrev_b32_e32 v94, 16, v217
	v_and_b32_e32 v95, 0xffff0000, v217
	v_pk_mul_f32 v[48:49], v[14:15], v[72:73]
	v_pk_mul_f32 v[56:57], v[22:23], v[80:81]
	v_pk_fma_f32 v[48:49], v[6:7], v[64:65], v[48:49]
	v_pk_add_f32 v[48:49], v[48:49], v[56:57]
	v_pk_add_f32 v[48:49], v[30:31], v[48:49]
	v_pk_mul_f32 v[48:49], v[48:49], v[88:89]
	v_pk_mul_f32 v[50:51], v[16:17], v[74:75]
	v_pk_mul_f32 v[56:57], v[24:25], v[82:83]
	v_pk_fma_f32 v[50:51], v[8:9], v[66:67], v[50:51]
	v_pk_add_f32 v[50:51], v[50:51], v[56:57]
	v_pk_add_f32 v[50:51], v[32:33], v[50:51]
	v_pk_mul_f32 v[50:51], v[50:51], v[90:91]
	v_pk_mul_f32 v[52:53], v[10:11], v[76:77]
	v_pk_mul_f32 v[56:57], v[18:19], v[84:85]
	v_pk_fma_f32 v[52:53], v[2:3], v[68:69], v[52:53]
	v_pk_add_f32 v[52:53], v[52:53], v[56:57]
	v_pk_add_f32 v[52:53], v[26:27], v[52:53]
	v_pk_mul_f32 v[52:53], v[52:53], v[92:93]
	v_pk_mul_f32 v[54:55], v[12:13], v[78:79]
	v_pk_mul_f32 v[56:57], v[20:21], v[86:87]
	v_pk_fma_f32 v[54:55], v[4:5], v[70:71], v[54:55]
	v_pk_add_f32 v[54:55], v[54:55], v[56:57]
	v_pk_add_f32 v[54:55], v[28:29], v[54:55]
	v_pk_mul_f32 v[54:55], v[54:55], v[94:95]
	v_cvt_pk_bf16_f32 v42, v48, v49
	v_cvt_pk_bf16_f32 v43, v50, v51
	v_cvt_pk_bf16_f32 v44, v52, v53
	v_cvt_pk_bf16_f32 v45, v54, v55
	global_store_dwordx4 v[40:41], v[42:45], off offset:2048
	s_waitcnt vmcnt(7)
; __device__ __forceinline__ unsigned cvt_pk_bf16(float lo, float hi) { unsigned r; asm volatile("v_cvt_pk_bf16_f32 %0, %1, %2" : "=v"(r) : "v"(lo), "v"(hi)); return r; }
; __device__ __forceinline__ void convbranch_phase(const bf16* proj, bf16* yc, const float* cw, const float* cb, int T, int vcu, int NT) {
;     ...
;         for (int t = t0; t < t0 + L; t += 4) {
;             const v4u z4 = (v4u){0u, 0u, 0u, 0u}; v4u un[4], gq[4];
; #pragma unroll
;             for (int q = 0; q < 4; ++q) { un[q] = z4; gq[q] = *(const v4u*)(p + (size_t)q * PW + C_GB);
;                 if (t + q + 1 < MC) un[q] = *(const v4u*)(p + (size_t)(q + 1) * PW + C_GCU); }
; #pragma unroll
;             for (int q = 0; q < 4; ++q) { const int tpos = (t + q) & (T - 1);
;                 float fg[8], pn[8], r[8]; unpack8(gq[q], fg); unpack8(un[q], pn);
;                 const float mp = tpos == 0 ? 0.f : 1.f, mn = tpos == T - 1 ? 0.f : 1.f;
; #pragma unroll
;                 for (int e = 0; e < 8; ++e) { r[e] = fg[e] * (w0[e] * (pp[e] * mp) + w1[e] * pc[e] + w2[e] * (pn[e] * mn) + bb[e]); pp[e] = pc[e]; pc[e] = pn[e]; }
;                 v4u o; o.x = cvt_pk_bf16(r[0], r[1]); o.y = cvt_pk_bf16(r[2], r[3]); o.z = cvt_pk_bf16(r[4], r[5]); o.w = cvt_pk_bf16(r[6], r[7]);
;                 *(v4u*)(yc + (size_t)(t + q) * AW + ch) = o; }
	v_lshlrev_b32_e32 v64, 16, v136
	v_and_b32_e32 v65, 0xffff0000, v136
	v_lshlrev_b32_e32 v66, 16, v137
	v_and_b32_e32 v67, 0xffff0000, v137
	v_lshlrev_b32_e32 v68, 16, v138
	v_and_b32_e32 v69, 0xffff0000, v138
	v_lshlrev_b32_e32 v70, 16, v139
	v_and_b32_e32 v71, 0xffff0000, v139
	v_lshlrev_b32_e32 v88, 16, v218
	v_and_b32_e32 v89, 0xffff0000, v218
	v_lshlrev_b32_e32 v90, 16, v219
	v_and_b32_e32 v91, 0xffff0000, v219
	v_lshlrev_b32_e32 v92, 16, v220
	v_and_b32_e32 v93, 0xffff0000, v220
	v_lshlrev_b32_e32 v94, 16, v221
	v_and_b32_e32 v95, 0xffff0000, v221
	v_pk_mul_f32 v[48:49], v[14:15], v[80:81]
	v_pk_mul_f32 v[56:57], v[22:23], v[64:65]
	v_pk_fma_f32 v[48:49], v[6:7], v[72:73], v[48:49]
	v_pk_add_f32 v[48:49], v[48:49], v[56:57]
	v_pk_add_f32 v[48:49], v[30:31], v[48:49]
	v_pk_mul_f32 v[48:49], v[48:49], v[88:89]
	v_pk_mul_f32 v[50:51], v[16:17], v[82:83]
	v_pk_mul_f32 v[56:57], v[24:25], v[66:67]
	v_pk_fma_f32 v[50:51], v[8:9], v[74:75], v[50:51]
	v_pk_add_f32 v[50:51], v[50:51], v[56:57]
	v_pk_add_f32 v[50:51], v[32:33], v[50:51]
	v_pk_mul_f32 v[50:51], v[50:51], v[90:91]
	v_pk_mul_f32 v[52:53], v[10:11], v[84:85]
	v_pk_mul_f32 v[56:57], v[18:19], v[68:69]
	v_pk_fma_f32 v[52:53], v[2:3], v[76:77], v[52:53]
	v_pk_add_f32 v[52:53], v[52:53], v[56:57]
	v_pk_add_f32 v[52:53], v[26:27], v[52:53]
	v_pk_mul_f32 v[52:53], v[52:53], v[92:93]
	v_pk_mul_f32 v[54:55], v[12:13], v[86:87]
	v_pk_mul_f32 v[56:57], v[20:21], v[70:71]
	v_pk_fma_f32 v[54:55], v[4:5], v[78:79], v[54:55]
	v_pk_add_f32 v[54:55], v[54:55], v[56:57]
	v_pk_add_f32 v[54:55], v[28:29], v[54:55]
	v_pk_mul_f32 v[54:55], v[54:55], v[94:95]
	v_cvt_pk_bf16_f32 v58, v48, v49
	v_cvt_pk_bf16_f32 v59, v50, v51
	v_cvt_pk_bf16_f32 v60, v52, v53
	v_cvt_pk_bf16_f32 v61, v54, v55
	global_store_dwordx4 v[40:41], v[58:61], off offset:3072
	global_load_dwordx4 v[140:143], v[36:37], off offset:3072
	v_add_co_u32_e32 v36, vcc, 0x2400, v36
	v_addc_co_u32_e32 v37, vcc, 0, v37, vcc
	global_load_dwordx4 v[104:107], v[36:37], off offset:2048
	global_load_dwordx4 v[144:147], v[36:37], off offset:3072
	v_add_co_u32_e32 v36, vcc, 0x2400, v36
	v_addc_co_u32_e32 v37, vcc, 0, v37, vcc
	global_load_dwordx4 v[108:111], v[36:37], off offset:2048
	global_load_dwordx4 v[148:151], v[36:37], off offset:3072
	v_add_co_u32_e32 v36, vcc, 0x2400, v36
	v_addc_co_u32_e32 v37, vcc, 0, v37, vcc
	global_load_dwordx4 v[112:115], v[36:37], off offset:2048
	global_load_dwordx4 v[156:159], v[36:37], off offset:3072
	v_add_co_u32_e32 v36, vcc, 0x2400, v36
	v_addc_co_u32_e32 v37, vcc, 0, v37, vcc
	global_load_dwordx4 v[116:119], v[36:37], off offset:2048
	global_load_dwordx4 v[174:177], v[36:37], off offset:3072
	v_add_co_u32_e32 v36, vcc, 0x2400, v36
	v_addc_co_u32_e32 v37, vcc, 0, v37, vcc
	global_load_dwordx4 v[120:123], v[36:37], off offset:2048
	global_load_dwordx4 v[204:207], v[36:37], off offset:3072
	v_add_co_u32_e32 v36, vcc, 0x2400, v36
	v_addc_co_u32_e32 v37, vcc, 0, v37, vcc
	global_load_dwordx4 v[124:127], v[36:37], off offset:2048
	global_load_dwordx4 v[214:217], v[36:37], off offset:3072
	v_add_co_u32_e32 v36, vcc, 0x2400, v36
	v_addc_co_u32_e32 v37, vcc, 0, v37, vcc
	global_load_dwordx4 v[128:131], v[36:37], off offset:2048
	global_load_dwordx4 v[218:221], v[36:37], off offset:3072
	s_waitcnt vmcnt(13)
	v_lshlrev_b32_e32 v72, 16, v104
	v_and_b32_e32 v73, 0xffff0000, v104
	v_lshlrev_b32_e32 v74, 16, v105
	v_and_b32_e32 v75, 0xffff0000, v105
	v_lshlrev_b32_e32 v76, 16, v106
	v_and_b32_e32 v77, 0xffff0000, v106
	v_lshlrev_b32_e32 v78, 16, v107
	v_and_b32_e32 v79, 0xffff0000, v107
	v_lshlrev_b32_e32 v88, 16, v140
	v_and_b32_e32 v89, 0xffff0000, v140
	v_lshlrev_b32_e32 v90, 16, v141
	v_and_b32_e32 v91, 0xffff0000, v141
	v_lshlrev_b32_e32 v92, 16, v142
	v_and_b32_e32 v93, 0xffff0000, v142
	v_lshlrev_b32_e32 v94, 16, v143
	v_and_b32_e32 v95, 0xffff0000, v143
	v_pk_mul_f32 v[48:49], v[14:15], v[64:65]
	v_pk_mul_f32 v[56:57], v[22:23], v[72:73]
	v_pk_fma_f32 v[48:49], v[6:7], v[80:81], v[48:49]
	v_pk_add_f32 v[48:49], v[48:49], v[56:57]
	v_pk_add_f32 v[48:49], v[30:31], v[48:49]
	v_pk_mul_f32 v[48:49], v[48:49], v[88:89]
	v_pk_mul_f32 v[50:51], v[16:17], v[66:67]
	v_pk_mul_f32 v[56:57], v[24:25], v[74:75]
	v_pk_fma_f32 v[50:51], v[8:9], v[82:83], v[50:51]
	v_pk_add_f32 v[50:51], v[50:51], v[56:57]
	v_pk_add_f32 v[50:51], v[32:33], v[50:51]
	v_pk_mul_f32 v[50:51], v[50:51], v[90:91]
	v_pk_mul_f32 v[52:53], v[10:11], v[68:69]
	v_pk_mul_f32 v[56:57], v[18:19], v[76:77]
	v_pk_fma_f32 v[52:53], v[2:3], v[84:85], v[52:53]
	v_pk_add_f32 v[52:53], v[52:53], v[56:57]
	v_pk_add_f32 v[52:53], v[26:27], v[52:53]
	v_pk_mul_f32 v[52:53], v[52:53], v[92:93]
	v_pk_mul_f32 v[54:55], v[12:13], v[70:71]
	v_pk_mul_f32 v[56:57], v[20:21], v[78:79]
	v_pk_fma_f32 v[54:55], v[4:5], v[86:87], v[54:55]
	v_pk_add_f32 v[54:55], v[54:55], v[56:57]
	v_pk_add_f32 v[54:55], v[28:29], v[54:55]
	v_pk_mul_f32 v[54:55], v[54:55], v[94:95]
	v_cvt_pk_bf16_f32 v42, v48, v49
	v_cvt_pk_bf16_f32 v43, v50, v51
	v_cvt_pk_bf16_f32 v44, v52, v53
	v_cvt_pk_bf16_f32 v45, v54, v55
	v_add_co_u32_e32 v40, vcc, 0x1000, v40
	v_addc_co_u32_e32 v41, vcc, 0, v41, vcc
	global_store_dwordx4 v[40:41], v[42:45], off
	s_waitcnt vmcnt(12)
; __device__ __forceinline__ unsigned cvt_pk_bf16(float lo, float hi) { unsigned r; asm volatile("v_cvt_pk_bf16_f32 %0, %1, %2" : "=v"(r) : "v"(lo), "v"(hi)); return r; }
; __device__ __forceinline__ void convbranch_phase(const bf16* proj, bf16* yc, const float* cw, const float* cb, int T, int vcu, int NT) {
;     ...
;             for (int q = 0; q < 4; ++q) { const int tpos = (t + q) & (T - 1);
;                 float fg[8], pn[8], r[8]; unpack8(gq[q], fg); unpack8(un[q], pn);
;                 const float mp = tpos == 0 ? 0.f : 1.f, mn = tpos == T - 1 ? 0.f : 1.f;
; #pragma unroll
;                 for (int e = 0; e < 8; ++e) { r[e] = fg[e] * (w0[e] * (pp[e] * mp) + w1[e] * pc[e] + w2[e] * (pn[e] * mn) + bb[e]); pp[e] = pc[e]; pc[e] = pn[e]; }
;                 v4u o; o.x = cvt_pk_bf16(r[0], r[1]); o.y = cvt_pk_bf16(r[2], r[3]); o.z = cvt_pk_bf16(r[4], r[5]); o.w = cvt_pk_bf16(r[6], r[7]);
;                 *(v4u*)(yc + (size_t)(t + q) * AW + ch) = o; }
	v_lshlrev_b32_e32 v80, 16, v108
	v_and_b32_e32 v81, 0xffff0000, v108
	v_lshlrev_b32_e32 v82, 16, v109
	v_and_b32_e32 v83, 0xffff0000, v109
	v_lshlrev_b32_e32 v84, 16, v110
	v_and_b32_e32 v85, 0xffff0000, v110
	v_lshlrev_b32_e32 v86, 16, v111
	v_and_b32_e32 v87, 0xffff0000, v111
	v_lshlrev_b32_e32 v88, 16, v144
	v_and_b32_e32 v89, 0xffff0000, v144
	v_lshlrev_b32_e32 v90, 16, v145
	v_and_b32_e32 v91, 0xffff0000, v145
	v_lshlrev_b32_e32 v92, 16, v146
	v_and_b32_e32 v93, 0xffff0000, v146
	v_lshlrev_b32_e32 v94, 16, v147
	v_and_b32_e32 v95, 0xffff0000, v147
	v_pk_mul_f32 v[48:49], v[14:15], v[72:73]
	v_pk_mul_f32 v[56:57], v[22:23], v[80:81]
	v_pk_fma_f32 v[48:49], v[6:7], v[64:65], v[48:49]
	v_pk_add_f32 v[48:49], v[48:49], v[56:57]
	v_pk_add_f32 v[48:49], v[30:31], v[48:49]
	v_pk_mul_f32 v[48:49], v[48:49], v[88:89]
	v_pk_mul_f32 v[50:51], v[16:17], v[74:75]
	v_pk_mul_f32 v[56:57], v[24:25], v[82:83]
	v_pk_fma_f32 v[50:51], v[8:9], v[66:67], v[50:51]
	v_pk_add_f32 v[50:51], v[50:51], v[56:57]
	v_pk_add_f32 v[50:51], v[32:33], v[50:51]
	v_pk_mul_f32 v[50:51], v[50:51], v[90:91]
	v_pk_mul_f32 v[52:53], v[10:11], v[76:77]
	v_pk_mul_f32 v[56:57], v[18:19], v[84:85]
	v_pk_fma_f32 v[52:53], v[2:3], v[68:69], v[52:53]
	v_pk_add_f32 v[52:53], v[52:53], v[56:57]
	v_pk_add_f32 v[52:53], v[26:27], v[52:53]
	v_pk_mul_f32 v[52:53], v[52:53], v[92:93]
	v_pk_mul_f32 v[54:55], v[12:13], v[78:79]
	v_pk_mul_f32 v[56:57], v[20:21], v[86:87]
	v_pk_fma_f32 v[54:55], v[4:5], v[70:71], v[54:55]
	v_pk_add_f32 v[54:55], v[54:55], v[56:57]
	v_pk_add_f32 v[54:55], v[28:29], v[54:55]
	v_pk_mul_f32 v[54:55], v[54:55], v[94:95]
	v_cvt_pk_bf16_f32 v58, v48, v49
	v_cvt_pk_bf16_f32 v59, v50, v51
	v_cvt_pk_bf16_f32 v60, v52, v53
	v_cvt_pk_bf16_f32 v61, v54, v55
	global_store_dwordx4 v[40:41], v[58:61], off offset:1024
	s_waitcnt vmcnt(11)
	v_lshlrev_b32_e32 v64, 16, v112
	v_and_b32_e32 v65, 0xffff0000, v112
	v_lshlrev_b32_e32 v66, 16, v113
	v_and_b32_e32 v67, 0xffff0000, v113
	v_lshlrev_b32_e32 v68, 16, v114
	v_and_b32_e32 v69, 0xffff0000, v114
	v_lshlrev_b32_e32 v70, 16, v115
	v_and_b32_e32 v71, 0xffff0000, v115
	v_lshlrev_b32_e32 v88, 16, v148
	v_and_b32_e32 v89, 0xffff0000, v148
	v_lshlrev_b32_e32 v90, 16, v149
	v_and_b32_e32 v91, 0xffff0000, v149
	v_lshlrev_b32_e32 v92, 16, v150
	v_and_b32_e32 v93, 0xffff0000, v150
	v_lshlrev_b32_e32 v94, 16, v151
	v_and_b32_e32 v95, 0xffff0000, v151
	v_pk_mul_f32 v[48:49], v[14:15], v[80:81]
	v_pk_mul_f32 v[56:57], v[22:23], v[64:65]
	v_pk_fma_f32 v[48:49], v[6:7], v[72:73], v[48:49]
	v_pk_add_f32 v[48:49], v[48:49], v[56:57]
	v_pk_add_f32 v[48:49], v[30:31], v[48:49]
	v_pk_mul_f32 v[48:49], v[48:49], v[88:89]
	v_pk_mul_f32 v[50:51], v[16:17], v[82:83]
	v_pk_mul_f32 v[56:57], v[24:25], v[66:67]
	v_pk_fma_f32 v[50:51], v[8:9], v[74:75], v[50:51]
	v_pk_add_f32 v[50:51], v[50:51], v[56:57]
	v_pk_add_f32 v[50:51], v[32:33], v[50:51]
	v_pk_mul_f32 v[50:51], v[50:51], v[90:91]
	v_pk_mul_f32 v[52:53], v[10:11], v[84:85]
	v_pk_mul_f32 v[56:57], v[18:19], v[68:69]
	v_pk_fma_f32 v[52:53], v[2:3], v[76:77], v[52:53]
	v_pk_add_f32 v[52:53], v[52:53], v[56:57]
	v_pk_add_f32 v[52:53], v[26:27], v[52:53]
	v_pk_mul_f32 v[52:53], v[52:53], v[92:93]
	v_pk_mul_f32 v[54:55], v[12:13], v[86:87]
	v_pk_mul_f32 v[56:57], v[20:21], v[70:71]
	v_pk_fma_f32 v[54:55], v[4:5], v[78:79], v[54:55]
	v_pk_add_f32 v[54:55], v[54:55], v[56:57]
	v_pk_add_f32 v[54:55], v[28:29], v[54:55]
	v_pk_mul_f32 v[54:55], v[54:55], v[94:95]
	v_cvt_pk_bf16_f32 v42, v48, v49
	v_cvt_pk_bf16_f32 v43, v50, v51
	v_cvt_pk_bf16_f32 v44, v52, v53
	v_cvt_pk_bf16_f32 v45, v54, v55
	global_store_dwordx4 v[40:41], v[42:45], off offset:2048
	s_waitcnt vmcnt(10)
	v_lshlrev_b32_e32 v72, 16, v116
	v_and_b32_e32 v73, 0xffff0000, v116
	v_lshlrev_b32_e32 v74, 16, v117
	v_and_b32_e32 v75, 0xffff0000, v117
	v_lshlrev_b32_e32 v76, 16, v118
	v_and_b32_e32 v77, 0xffff0000, v118
	v_lshlrev_b32_e32 v78, 16, v119
	v_and_b32_e32 v79, 0xffff0000, v119
	v_lshlrev_b32_e32 v88, 16, v156
	v_and_b32_e32 v89, 0xffff0000, v156
	v_lshlrev_b32_e32 v90, 16, v157
	v_and_b32_e32 v91, 0xffff0000, v157
	v_lshlrev_b32_e32 v92, 16, v158
	v_and_b32_e32 v93, 0xffff0000, v158
	v_lshlrev_b32_e32 v94, 16, v159
	v_and_b32_e32 v95, 0xffff0000, v159
	v_pk_mul_f32 v[48:49], v[14:15], v[64:65]
	v_pk_mul_f32 v[56:57], v[22:23], v[72:73]
	v_pk_fma_f32 v[48:49], v[6:7], v[80:81], v[48:49]
	v_pk_add_f32 v[48:49], v[48:49], v[56:57]
	v_pk_add_f32 v[48:49], v[30:31], v[48:49]
	v_pk_mul_f32 v[48:49], v[48:49], v[88:89]
	v_pk_mul_f32 v[50:51], v[16:17], v[66:67]
	v_pk_mul_f32 v[56:57], v[24:25], v[74:75]
	v_pk_fma_f32 v[50:51], v[8:9], v[82:83], v[50:51]
	v_pk_add_f32 v[50:51], v[50:51], v[56:57]
	v_pk_add_f32 v[50:51], v[32:33], v[50:51]
	v_pk_mul_f32 v[50:51], v[50:51], v[90:91]
	v_pk_mul_f32 v[52:53], v[10:11], v[68:69]
	v_pk_mul_f32 v[56:57], v[18:19], v[76:77]
	v_pk_fma_f32 v[52:53], v[2:3], v[84:85], v[52:53]
	v_pk_add_f32 v[52:53], v[52:53], v[56:57]
	v_pk_add_f32 v[52:53], v[26:27], v[52:53]
	v_pk_mul_f32 v[52:53], v[52:53], v[92:93]
	v_pk_mul_f32 v[54:55], v[12:13], v[70:71]
	v_pk_mul_f32 v[56:57], v[20:21], v[78:79]
	v_pk_fma_f32 v[54:55], v[4:5], v[86:87], v[54:55]
	v_pk_add_f32 v[54:55], v[54:55], v[56:57]
	v_pk_add_f32 v[54:55], v[28:29], v[54:55]
	v_pk_mul_f32 v[54:55], v[54:55], v[94:95]
	v_cvt_pk_bf16_f32 v58, v48, v49
	v_cvt_pk_bf16_f32 v59, v50, v51
	v_cvt_pk_bf16_f32 v60, v52, v53
	v_cvt_pk_bf16_f32 v61, v54, v55
	global_store_dwordx4 v[40:41], v[58:61], off offset:3072
	s_waitcnt vmcnt(9)
; __device__ __forceinline__ unsigned cvt_pk_bf16(float lo, float hi) { unsigned r; asm volatile("v_cvt_pk_bf16_f32 %0, %1, %2" : "=v"(r) : "v"(lo), "v"(hi)); return r; }
; __device__ __forceinline__ void convbranch_phase(const bf16* proj, bf16* yc, const float* cw, const float* cb, int T, int vcu, int NT) {
;     ...
;             for (int q = 0; q < 4; ++q) { const int tpos = (t + q) & (T - 1);
;                 float fg[8], pn[8], r[8]; unpack8(gq[q], fg); unpack8(un[q], pn);
;                 const float mp = tpos == 0 ? 0.f : 1.f, mn = tpos == T - 1 ? 0.f : 1.f;
; #pragma unroll
;                 for (int e = 0; e < 8; ++e) { r[e] = fg[e] * (w0[e] * (pp[e] * mp) + w1[e] * pc[e] + w2[e] * (pn[e] * mn) + bb[e]); pp[e] = pc[e]; pc[e] = pn[e]; }
;                 v4u o; o.x = cvt_pk_bf16(r[0], r[1]); o.y = cvt_pk_bf16(r[2], r[3]); o.z = cvt_pk_bf16(r[4], r[5]); o.w = cvt_pk_bf16(r[6], r[7]);
;                 *(v4u*)(yc + (size_t)(t + q) * AW + ch) = o; }
	v_lshlrev_b32_e32 v80, 16, v120
	v_and_b32_e32 v81, 0xffff0000, v120
	v_lshlrev_b32_e32 v82, 16, v121
	v_and_b32_e32 v83, 0xffff0000, v121
	v_lshlrev_b32_e32 v84, 16, v122
	v_and_b32_e32 v85, 0xffff0000, v122
	v_lshlrev_b32_e32 v86, 16, v123
	v_and_b32_e32 v87, 0xffff0000, v123
	v_lshlrev_b32_e32 v88, 16, v174
	v_and_b32_e32 v89, 0xffff0000, v174
	v_lshlrev_b32_e32 v90, 16, v175
	v_and_b32_e32 v91, 0xffff0000, v175
	v_lshlrev_b32_e32 v92, 16, v176
	v_and_b32_e32 v93, 0xffff0000, v176
	v_lshlrev_b32_e32 v94, 16, v177
	v_and_b32_e32 v95, 0xffff0000, v177
	v_pk_mul_f32 v[48:49], v[14:15], v[72:73]
	v_pk_mul_f32 v[56:57], v[22:23], v[80:81]
	v_pk_fma_f32 v[48:49], v[6:7], v[64:65], v[48:49]
	v_pk_add_f32 v[48:49], v[48:49], v[56:57]
	v_pk_add_f32 v[48:49], v[30:31], v[48:49]
	v_pk_mul_f32 v[48:49], v[48:49], v[88:89]
	v_pk_mul_f32 v[50:51], v[16:17], v[74:75]
	v_pk_mul_f32 v[56:57], v[24:25], v[82:83]
	v_pk_fma_f32 v[50:51], v[8:9], v[66:67], v[50:51]
	v_pk_add_f32 v[50:51], v[50:51], v[56:57]
	v_pk_add_f32 v[50:51], v[32:33], v[50:51]
	v_pk_mul_f32 v[50:51], v[50:51], v[90:91]
	v_pk_mul_f32 v[52:53], v[10:11], v[76:77]
	v_pk_mul_f32 v[56:57], v[18:19], v[84:85]
	v_pk_fma_f32 v[52:53], v[2:3], v[68:69], v[52:53]
	v_pk_add_f32 v[52:53], v[52:53], v[56:57]
	v_pk_add_f32 v[52:53], v[26:27], v[52:53]
	v_pk_mul_f32 v[52:53], v[52:53], v[92:93]
	v_pk_mul_f32 v[54:55], v[12:13], v[78:79]
	v_pk_mul_f32 v[56:57], v[20:21], v[86:87]
	v_pk_fma_f32 v[54:55], v[4:5], v[70:71], v[54:55]
	v_pk_add_f32 v[54:55], v[54:55], v[56:57]
	v_pk_add_f32 v[54:55], v[28:29], v[54:55]
	v_pk_mul_f32 v[54:55], v[54:55], v[94:95]
	v_cvt_pk_bf16_f32 v42, v48, v49
	v_cvt_pk_bf16_f32 v43, v50, v51
	v_cvt_pk_bf16_f32 v44, v52, v53
	v_cvt_pk_bf16_f32 v45, v54, v55
	v_add_co_u32_e32 v40, vcc, 0x1000, v40
	v_addc_co_u32_e32 v41, vcc, 0, v41, vcc
	global_store_dwordx4 v[40:41], v[42:45], off
	s_waitcnt vmcnt(8)
	v_lshlrev_b32_e32 v64, 16, v124
	v_and_b32_e32 v65, 0xffff0000, v124
	v_lshlrev_b32_e32 v66, 16, v125
	v_and_b32_e32 v67, 0xffff0000, v125
	v_lshlrev_b32_e32 v68, 16, v126
	v_and_b32_e32 v69, 0xffff0000, v126
	v_lshlrev_b32_e32 v70, 16, v127
	v_and_b32_e32 v71, 0xffff0000, v127
	v_lshlrev_b32_e32 v88, 16, v204
	v_and_b32_e32 v89, 0xffff0000, v204
	v_lshlrev_b32_e32 v90, 16, v205
	v_and_b32_e32 v91, 0xffff0000, v205
	v_lshlrev_b32_e32 v92, 16, v206
	v_and_b32_e32 v93, 0xffff0000, v206
	v_lshlrev_b32_e32 v94, 16, v207
	v_and_b32_e32 v95, 0xffff0000, v207
	v_pk_mul_f32 v[48:49], v[14:15], v[80:81]
	v_pk_mul_f32 v[56:57], v[22:23], v[64:65]
	v_pk_fma_f32 v[48:49], v[6:7], v[72:73], v[48:49]
	v_pk_add_f32 v[48:49], v[48:49], v[56:57]
	v_pk_add_f32 v[48:49], v[30:31], v[48:49]
	v_pk_mul_f32 v[48:49], v[48:49], v[88:89]
	v_pk_mul_f32 v[50:51], v[16:17], v[82:83]
	v_pk_mul_f32 v[56:57], v[24:25], v[66:67]
	v_pk_fma_f32 v[50:51], v[8:9], v[74:75], v[50:51]
	v_pk_add_f32 v[50:51], v[50:51], v[56:57]
	v_pk_add_f32 v[50:51], v[32:33], v[50:51]
	v_pk_mul_f32 v[50:51], v[50:51], v[90:91]
	v_pk_mul_f32 v[52:53], v[10:11], v[84:85]
	v_pk_mul_f32 v[56:57], v[18:19], v[68:69]
	v_pk_fma_f32 v[52:53], v[2:3], v[76:77], v[52:53]
	v_pk_add_f32 v[52:53], v[52:53], v[56:57]
	v_pk_add_f32 v[52:53], v[26:27], v[52:53]
	v_pk_mul_f32 v[52:53], v[52:53], v[92:93]
	v_pk_mul_f32 v[54:55], v[12:13], v[86:87]
	v_pk_mul_f32 v[56:57], v[20:21], v[70:71]
	v_pk_fma_f32 v[54:55], v[4:5], v[78:79], v[54:55]
	v_pk_add_f32 v[54:55], v[54:55], v[56:57]
	v_pk_add_f32 v[54:55], v[28:29], v[54:55]
	v_pk_mul_f32 v[54:55], v[54:55], v[94:95]
	v_cvt_pk_bf16_f32 v58, v48, v49
	v_cvt_pk_bf16_f32 v59, v50, v51
	v_cvt_pk_bf16_f32 v60, v52, v53
	v_cvt_pk_bf16_f32 v61, v54, v55
	global_store_dwordx4 v[40:41], v[58:61], off offset:1024
	s_waitcnt vmcnt(7)
; __device__ __forceinline__ unsigned cvt_pk_bf16(float lo, float hi) { unsigned r; asm volatile("v_cvt_pk_bf16_f32 %0, %1, %2" : "=v"(r) : "v"(lo), "v"(hi)); return r; }
; __device__ __forceinline__ void convbranch_phase(const bf16* proj, bf16* yc, const float* cw, const float* cb, int T, int vcu, int NT) {
;     ...
;             for (int q = 0; q < 4; ++q) { const int tpos = (t + q) & (T - 1);
;                 float fg[8], pn[8], r[8]; unpack8(gq[q], fg); unpack8(un[q], pn);
;                 const float mp = tpos == 0 ? 0.f : 1.f, mn = tpos == T - 1 ? 0.f : 1.f;
; #pragma unroll
;                 for (int e = 0; e < 8; ++e) { r[e] = fg[e] * (w0[e] * (pp[e] * mp) + w1[e] * pc[e] + w2[e] * (pn[e] * mn) + bb[e]); pp[e] = pc[e]; pc[e] = pn[e]; }
;                 v4u o; o.x = cvt_pk_bf16(r[0], r[1]); o.y = cvt_pk_bf16(r[2], r[3]); o.z = cvt_pk_bf16(r[4], r[5]); o.w = cvt_pk_bf16(r[6], r[7]);
;                 *(v4u*)(yc + (size_t)(t + q) * AW + ch) = o; }
;             p += 4 * (size_t)PW;
	v_lshlrev_b32_e32 v72, 16, v128
	v_and_b32_e32 v73, 0xffff0000, v128
	v_lshlrev_b32_e32 v74, 16, v129
	v_and_b32_e32 v75, 0xffff0000, v129
	v_lshlrev_b32_e32 v76, 16, v130
	v_and_b32_e32 v77, 0xffff0000, v130
	v_lshlrev_b32_e32 v78, 16, v131
	v_and_b32_e32 v79, 0xffff0000, v131
	v_lshlrev_b32_e32 v88, 16, v214
	v_and_b32_e32 v89, 0xffff0000, v214
	v_lshlrev_b32_e32 v90, 16, v215
	v_and_b32_e32 v91, 0xffff0000, v215
	v_lshlrev_b32_e32 v92, 16, v216
	v_and_b32_e32 v93, 0xffff0000, v216
	v_lshlrev_b32_e32 v94, 16, v217
	v_and_b32_e32 v95, 0xffff0000, v217
	v_pk_mul_f32 v[48:49], v[14:15], v[64:65]
	v_pk_mul_f32 v[56:57], v[22:23], v[72:73]
	v_pk_fma_f32 v[48:49], v[6:7], v[80:81], v[48:49]
	v_pk_add_f32 v[48:49], v[48:49], v[56:57]
	v_pk_add_f32 v[48:49], v[30:31], v[48:49]
	v_pk_mul_f32 v[48:49], v[48:49], v[88:89]
	v_pk_mul_f32 v[50:51], v[16:17], v[66:67]
	v_pk_mul_f32 v[56:57], v[24:25], v[74:75]
	v_pk_fma_f32 v[50:51], v[8:9], v[82:83], v[50:51]
	v_pk_add_f32 v[50:51], v[50:51], v[56:57]
	v_pk_add_f32 v[50:51], v[32:33], v[50:51]
	v_pk_mul_f32 v[50:51], v[50:51], v[90:91]
	v_pk_mul_f32 v[52:53], v[10:11], v[68:69]
	v_pk_mul_f32 v[56:57], v[18:19], v[76:77]
	v_pk_fma_f32 v[52:53], v[2:3], v[84:85], v[52:53]
	v_pk_add_f32 v[52:53], v[52:53], v[56:57]
	v_pk_add_f32 v[52:53], v[26:27], v[52:53]
	v_pk_mul_f32 v[52:53], v[52:53], v[92:93]
	v_pk_mul_f32 v[54:55], v[12:13], v[70:71]
	v_pk_mul_f32 v[56:57], v[20:21], v[78:79]
	v_pk_fma_f32 v[54:55], v[4:5], v[86:87], v[54:55]
	v_pk_add_f32 v[54:55], v[54:55], v[56:57]
	v_pk_add_f32 v[54:55], v[28:29], v[54:55]
	v_pk_mul_f32 v[54:55], v[54:55], v[94:95]
	v_cvt_pk_bf16_f32 v42, v48, v49
	v_cvt_pk_bf16_f32 v43, v50, v51
	v_cvt_pk_bf16_f32 v44, v52, v53
	v_cvt_pk_bf16_f32 v45, v54, v55
	global_store_dwordx4 v[40:41], v[42:45], off offset:2048
	s_waitcnt vmcnt(7)
	v_lshlrev_b32_e32 v80, 16, v100
	v_and_b32_e32 v81, 0xffff0000, v100
	v_lshlrev_b32_e32 v82, 16, v101
	v_and_b32_e32 v83, 0xffff0000, v101
	v_lshlrev_b32_e32 v84, 16, v102
	v_and_b32_e32 v85, 0xffff0000, v102
	v_lshlrev_b32_e32 v86, 16, v103
	v_and_b32_e32 v87, 0xffff0000, v103
	v_lshlrev_b32_e32 v88, 16, v218
	v_and_b32_e32 v89, 0xffff0000, v218
	v_lshlrev_b32_e32 v90, 16, v219
	v_and_b32_e32 v91, 0xffff0000, v219
	v_lshlrev_b32_e32 v92, 16, v220
	v_and_b32_e32 v93, 0xffff0000, v220
	v_lshlrev_b32_e32 v94, 16, v221
	v_and_b32_e32 v95, 0xffff0000, v221
	v_pk_mul_f32 v[48:49], v[14:15], v[72:73]
	v_pk_mul_f32 v[56:57], v[22:23], v[80:81]
	v_pk_fma_f32 v[48:49], v[6:7], v[64:65], v[48:49]
	v_pk_add_f32 v[48:49], v[48:49], v[56:57]
	v_pk_add_f32 v[48:49], v[30:31], v[48:49]
	v_pk_mul_f32 v[48:49], v[48:49], v[88:89]
	v_pk_mul_f32 v[50:51], v[16:17], v[74:75]
	v_pk_mul_f32 v[56:57], v[24:25], v[82:83]
	v_pk_fma_f32 v[50:51], v[8:9], v[66:67], v[50:51]
	v_pk_add_f32 v[50:51], v[50:51], v[56:57]
	v_pk_add_f32 v[50:51], v[32:33], v[50:51]
	v_pk_mul_f32 v[50:51], v[50:51], v[90:91]
	v_pk_mul_f32 v[52:53], v[10:11], v[76:77]
	v_pk_mul_f32 v[56:57], v[18:19], v[84:85]
	v_pk_fma_f32 v[52:53], v[2:3], v[68:69], v[52:53]
	v_pk_add_f32 v[52:53], v[52:53], v[56:57]
	v_pk_add_f32 v[52:53], v[26:27], v[52:53]
	v_pk_mul_f32 v[52:53], v[52:53], v[92:93]
	v_pk_mul_f32 v[54:55], v[12:13], v[78:79]
	v_pk_mul_f32 v[56:57], v[20:21], v[86:87]
	v_pk_fma_f32 v[54:55], v[4:5], v[70:71], v[54:55]
	v_pk_add_f32 v[54:55], v[54:55], v[56:57]
	v_pk_add_f32 v[54:55], v[28:29], v[54:55]
	v_pk_mul_f32 v[54:55], v[54:55], v[94:95]
	v_cvt_pk_bf16_f32 v58, v48, v49
	v_cvt_pk_bf16_f32 v59, v50, v51
	v_cvt_pk_bf16_f32 v60, v52, v53
	v_cvt_pk_bf16_f32 v61, v54, v55
	global_store_dwordx4 v[40:41], v[58:61], off offset:3072
	s_mov_b64 s[40:41], 0
	s_branch .LBB0_565
